# copy workers stop taking new cache-copy items once the first GEMM workgroup of the phase is done (no item overshoots the phase end); leftovers still copied in final phase
# speedup vs baseline: 1.0251x; 1.0226x over previous
.LBB0_281:
	s_and_saveexec_b64 s[20:21], s[36:37]
	s_cbranch_execz .LBB0_289
	s_and_b64 vcc, exec, s[8:9]
	s_mov_b64 s[22:23], s[16:17]
	s_cbranch_vccnz .LBB0_284
	global_load_dword v0, v129, s[18:19] sc1
	s_waitcnt vmcnt(0)
	v_cmp_gt_i32_e64 s[22:23], 1, v0

.LBB0_1109:
	s_and_saveexec_b64 s[20:21], s[36:37]
	s_cbranch_execz .LBB0_1117
	s_and_b64 vcc, exec, s[8:9]
	s_mov_b64 s[22:23], s[10:11]
	s_cbranch_vccnz .LBB0_1112
	global_load_dword v0, v129, s[18:19] sc1
	s_waitcnt vmcnt(0)
	v_cmp_gt_i32_e64 s[22:23], 1, v0

.LBB0_1276:
	s_and_saveexec_b64 s[18:19], s[36:37]
	s_cbranch_execz .LBB0_1284
	s_and_b64 vcc, exec, s[8:9]
	s_mov_b64 s[20:21], s[10:11]
	s_cbranch_vccnz .LBB0_1279
	global_load_dword v0, v129, s[16:17] sc1
	s_waitcnt vmcnt(0)
	v_cmp_gt_i32_e64 s[20:21], 1, v0
